# P4 work queue hands out SSD pass-C units interleaved 1:2 with prompt-attention units instead of all at the end (on top of attention softmax/LDS rework and pass C state prefetch)
# speedup vs baseline: 1.0063x; 1.0031x over previous
; #define LAS __attribute__((address_space(3)))
; template <bool PASS_A>
; __device__ __forceinline__ void ssd_scalars(const Params& p, LAS unsigned char* lds, int ci, int g, int wave, int lane) {
;     const int h = 8 * g + wave;
;     const float dtv = ((const float*)(p.ws + WS_DT))[(size_t)(64 * ci + lane) * 16 + h];
;     const float A = -__expf(p.in[15][h]);
;     float c = dtv * A;
; #pragma unroll
;     for (int o = 1; o < 64; o <<= 1) { const float t = __shfl_up(c, o); if (lane >= o) c += t; }
;     const float last = __shfl(c, 63);
;     LAS float* sdt = (LAS float*)(lds + L_DT) + wave * 64; LAS float* scum = (LAS float*)(lds + L_CUM) + wave * 64;
;     if (PASS_A) { sdt[lane] = dtv * __expf(last - c); if (lane == 0) ((float*)(p.ws + WS_DEC))[ci * 16 + h] = __expf(last); }
;     else { sdt[lane] = dtv; scum[lane] = c; }
; }
; __global__ void __launch_bounds__(NTHR, 2) fwd_megakernel(Params p) {
;     ...
;             __syncthreads();
;             if (tid == 0) *sw = (int)atomicAdd(ctr, 1u);
;             __syncthreads();
;             const int u = *sw;
;             if (u >= (rep4 == 0 ? N_ATT_S + N_ATT_P + N_SSD : REP_P4_NU)) break;
;     ...
;             if (u < N_ATT_S) attn_unit<true>(p, lds, u, tid, lane, wave, thr);
;             else if (u < N_ATT_S + N_ATT_P) attn_unit<false>(p, lds, u - N_ATT_S, tid, lane, wave, thr);
;             else ssd_pass_c(p, lds, u - N_ATT_S - N_ATT_P, tid, lane, wave);
.LBB0_554:
	s_or_b64 exec, exec, s[2:3]
	s_waitcnt lgkmcnt(0)
	s_barrier
	ds_read_b32 v2, v221
	s_movk_i32 s2, 0xc9f
	s_waitcnt lgkmcnt(0)
	v_cmp_lt_i32_e32 vcc, s2, v2
	v_readfirstlane_b32 s57, v2
	s_mov_b64 s[2:3], -1
	s_cbranch_vccnz .LBB0_549
	s_cmpk_gt_i32 s57, 0x7f
	s_cbranch_scc0 .LBB0_625
	s_sub_i32 s4, s57, 0x80
	s_cmpk_gt_u32 s4, 0xbff
	s_cbranch_scc1 .Lq_nomap
	s_mul_hi_u32 s5, s4, 0xaaaaaaab
	s_lshr_b32 s5, s5, 1
	s_mul_i32 s6, s5, 3
	s_sub_i32 s6, s4, s6
	s_cmp_eq_u32 s6, 2
	s_cbranch_scc1 .Lq_passc
	s_lshl_b32 s5, s5, 1
	s_add_i32 s5, s5, s6
	s_add_i32 s57, s5, 0x80
	s_branch .Lq_nomap
.Lq_passc:
	s_add_i32 s57, s5, 0x880
.Lq_nomap:
	s_cmpk_gt_u32 s57, 0x87f
	s_cbranch_scc0 .LBB0_598
	s_add_i32 s4, s57, 0xfffff780
	s_lshr_b32 s5, s4, 1
	s_and_b32 s14, s57, 1
	v_mov_b32_e32 v3, v0
	s_mov_b32 s11, s85
	v_mov_b32_e32 v2, v195
	s_lshl_b32 s2, s14, 3
	s_lshl_b32 s34, s5, 6
	s_add_i32 s8, s11, s2
	v_add_u32_e32 v6, s34, v2
	v_ashrrev_i32_e32 v7, 31, v6
	s_ashr_i32 s9, s8, 31
	v_readlane_b32 s2, v254, 57
	v_lshlrev_b64 v[6:7], 6, v[6:7]
	v_readlane_b32 s3, v254, 58
	s_lshl_b64 s[6:7], s[8:9], 2
	s_nop 0
	v_lshl_add_u64 v[6:7], s[2:3], 0, v[6:7]
	s_add_u32 s2, s82, s6
	v_lshl_add_u64 v[6:7], v[6:7], 0, s[6:7]
	s_addc_u32 s3, s83, s7
	s_barrier
	global_load_dword v5, v[6:7], off
	v_cmp_lt_i32_e32 vcc, v222, v217
	global_load_dword v6, v4, s[2:3]
	s_lshl_b32 s2, s11, 8
	v_cndmask_b32_e32 v8, v222, v216, vcc
	v_lshlrev_b32_e32 v8, 2, v8
	v_cmp_gt_i32_e32 vcc, 1, v2
	s_add_i32 s59, s2, 0
	s_add_i32 s58, s59, 0x1ac00
	s_add_i32 s59, s59, 0x1b400
	s_mov_b64 s[2:3], -1
	s_cmpk_gt_u32 s4, 0x3ff
	s_waitcnt vmcnt(0)
	v_mul_f32_e32 v6, 0x3fb8aa3b, v6
	v_exp_f32_e32 v6, v6
	s_nop 0
	v_mul_f32_e64 v7, v5, -v6
	ds_bpermute_b32 v8, v8, v7
	s_waitcnt lgkmcnt(0)
	v_fma_f32 v6, v5, -v6, v8
	v_cndmask_b32_e32 v6, v6, v7, vcc
	v_cmp_lt_i32_e32 vcc, v223, v217
	s_nop 1
	v_cndmask_b32_e32 v7, v223, v216, vcc
	v_lshlrev_b32_e32 v7, 2, v7
	ds_bpermute_b32 v7, v7, v6
	v_cmp_gt_i32_e32 vcc, 2, v2
	s_waitcnt lgkmcnt(0)
	v_add_f32_e32 v7, v6, v7
	v_cndmask_b32_e32 v6, v7, v6, vcc
	v_cmp_lt_i32_e32 vcc, v224, v217
	s_nop 1
	v_cndmask_b32_e32 v7, v224, v216, vcc
	v_lshlrev_b32_e32 v7, 2, v7
	ds_bpermute_b32 v7, v7, v6
	v_cmp_gt_i32_e32 vcc, 4, v2
	s_waitcnt lgkmcnt(0)
	v_add_f32_e32 v7, v6, v7
	v_cndmask_b32_e32 v6, v7, v6, vcc
	v_cmp_lt_i32_e32 vcc, v225, v217
	s_nop 1
	v_cndmask_b32_e32 v7, v225, v216, vcc
	v_lshlrev_b32_e32 v7, 2, v7
	ds_bpermute_b32 v7, v7, v6
	v_cmp_gt_i32_e32 vcc, 8, v2
	s_waitcnt lgkmcnt(0)
	v_add_f32_e32 v7, v6, v7
	v_cndmask_b32_e32 v6, v7, v6, vcc
	v_cmp_lt_i32_e32 vcc, v226, v217
	s_nop 1
	v_cndmask_b32_e32 v7, v226, v216, vcc
	v_lshlrev_b32_e32 v7, 2, v7
	ds_bpermute_b32 v7, v7, v6
	v_cmp_gt_i32_e32 vcc, 16, v2
	s_waitcnt lgkmcnt(0)
	v_add_f32_e32 v7, v6, v7
	v_cndmask_b32_e32 v6, v7, v6, vcc
	v_cmp_lt_i32_e32 vcc, v227, v217
	s_nop 1
	v_cndmask_b32_e32 v7, v227, v216, vcc
	v_lshlrev_b32_e32 v7, 2, v7
	ds_bpermute_b32 v7, v7, v6
	v_cmp_gt_i32_e32 vcc, 32, v2
	s_waitcnt lgkmcnt(0)
	v_add_f32_e32 v7, v6, v7
	v_cndmask_b32_e32 v6, v7, v6, vcc
	v_lshlrev_b32_e32 v7, 2, v2
	v_add_u32_e32 v8, s58, v7
	ds_write_b32 v8, v5
	v_add_u32_e32 v5, s59, v7
	ds_write_b32 v5, v6
	s_cbranch_scc0 .LBB0_560
	s_lshl_b32 s2, s5, 4
	s_add_i32 s10, s8, s2
	s_cbranch_execz .LBB0_561
